# gla_a/gla_c: the next-unit L2 warm-up loads removed (every real load is now issued stages ahead; the warm-ups only added request traffic)
# speedup vs baseline: 1.0308x; 1.0075x over previous
.LBB0_655:
	s_or_b64 exec, exec, s[0:1]
	v_add_u32_e32 v24, s45, v34
	v_mov_b32_e32 v25, v31
	v_lshl_add_u64 v[24:25], v[24:25], 2, s[90:91]
	v_mov_b32_e32 v23, v211
	v_mfma_f32_16x16x32_bf16 v[16:19], v[16:19], v[4:7], 0
	v_add_u32_e32 v129, 0x800, v127
	v_add_u32_e32 v130, 0xc00, v127
	v_add_u32_e32 v132, 0x1000, v127
	v_mfma_f32_16x16x32_bf16 v[12:15], v[12:15], v[4:7], 0
	v_add_u32_e32 v135, 0x1400, v127
	v_add_u32_e32 v138, 0x1800, v127
	v_add_u32_e32 v133, 0x1c00, v127
	v_mfma_f32_16x16x32_bf16 v[8:11], v[8:11], v[4:7], 0
	v_add_u32_e32 v136, 0x2000, v127
	v_add_u32_e32 v139, 0x2400, v127
	v_add_u32_e32 v141, 0x2800, v127
	v_mfma_f32_16x16x32_bf16 v[0:3], v[0:3], v[4:7], 0
	v_add_u32_e32 v142, 0x2c00, v127
	v_add_u32_e32 v140, 0x3000, v127
	v_add_u32_e32 v137, 0x3400, v127
	v_add_u32_e32 v134, 0x3800, v127
	v_add_u32_e32 v131, 0x3c00, v127
.Lpf_a_skip:
	v_add_f32_e32 v16, v23, v16
	v_add_f32_e32 v17, v23, v17
	v_min_f32_e32 v24, 0, v16
	v_mul_f32_e64 v16, |v16|, s38
	v_add_f32_e32 v18, v23, v18
	v_min_f32_e32 v25, 0, v17
	v_mul_f32_e64 v17, |v17|, s38
	v_exp_f32_e32 v16, v16
	v_add_f32_e32 v19, v23, v19
	v_min_f32_e32 v26, 0, v18
	v_mul_f32_e64 v18, |v18|, s38
	v_exp_f32_e32 v17, v17
	v_min_f32_e32 v27, 0, v19
	v_mul_f32_e64 v19, |v19|, s38
	v_exp_f32_e32 v18, v18
	v_exp_f32_e32 v19, v19
	v_add_f32_e32 v16, 1.0, v16
	v_add_f32_e32 v12, v23, v12
	v_add_f32_e32 v17, 1.0, v17
	v_min_f32_e32 v43, 0, v12
	v_mul_f32_e64 v12, |v12|, s38
	v_add_f32_e32 v18, 1.0, v18
	v_exp_f32_e32 v12, v12
	v_add_f32_e32 v19, 1.0, v19
	v_log_f32_e32 v16, v16
	v_log_f32_e32 v17, v17
	v_log_f32_e32 v18, v18
	v_add_f32_e32 v12, 1.0, v12
	v_log_f32_e32 v19, v19
	v_log_f32_e32 v12, v12
	v_add_f32_e32 v13, v23, v13
	v_mul_f32_e64 v44, |v13|, s38
	v_exp_f32_e32 v44, v44
	v_fma_f32 v16, -v16, s40, v24
	v_fma_f32 v17, -v17, s40, v25
	v_fma_f32 v18, -v18, s40, v26
	v_fma_f32 v19, -v19, s40, v27
	v_mul_f32_e32 v16, 0x3d800000, v16
	v_mul_f32_e32 v17, 0x3d800000, v17
	v_mul_f32_e32 v18, 0x3d800000, v18
	v_mul_f32_e32 v19, 0x3d800000, v19
	ds_write2_b32 v126, v16, v17 offset0:16 offset1:145
	ds_write2_b32 v28, v18, v19 offset0:18 offset1:147
	v_add_f32_e32 v16, 1.0, v44
	v_add_f32_e32 v14, v23, v14
	v_min_f32_e32 v13, 0, v13
	v_log_f32_e32 v16, v16
	v_fma_f32 v12, -v12, s40, v43
	v_mul_f32_e32 v12, 0x3d800000, v12
	v_mul_f32_e64 v17, |v14|, s38
	v_exp_f32_e32 v17, v17
	v_fma_f32 v13, -v16, s40, v13
	v_mul_f32_e32 v13, 0x3d800000, v13
	v_add_f32_e32 v16, 1.0, v17
	ds_write2_b32 v29, v12, v13 offset0:32 offset1:161
	v_min_f32_e32 v12, 0, v14
	v_log_f32_e32 v16, v16
	v_add_f32_e32 v14, v23, v15
	v_mul_f32_e64 v15, |v14|, s38
	v_exp_f32_e32 v15, v15
	s_nop 0
	v_add_f32_e32 v15, 1.0, v15
	v_add_f32_e32 v8, v23, v8
	v_cmp_gt_f32_e32 vcc, s39, v15
	v_fma_f32 v12, -v16, s40, v12
	v_cndmask_b32_e64 v16, 0, 32, vcc
	v_ldexp_f32 v15, v15, v16
	v_log_f32_e32 v15, v15
	v_min_f32_e32 v13, 0, v14
	v_cndmask_b32_e32 v16, 0, v125, vcc
	v_mul_f32_e32 v12, 0x3d800000, v12
	v_mul_f32_e32 v14, 0x3f317217, v15
	v_fma_f32 v14, v15, s40, -v14
	v_fmac_f32_e32 v14, 0x3377d1cf, v15
	v_fmac_f32_e32 v14, 0x3f317217, v15
	v_cmp_lt_f32_e64 s[0:1], |v15|, s41
	v_add_f32_e32 v9, v23, v9
	v_add_f32_e32 v10, v23, v10
	v_cndmask_b32_e64 v14, v15, v14, s[0:1]
	v_mul_f32_e64 v15, |v8|, s38
	v_exp_f32_e32 v15, v15
	v_sub_f32_e32 v14, v14, v16
	v_sub_f32_e32 v13, v13, v14
	v_mul_f32_e32 v13, 0x3d800000, v13
	v_add_f32_e32 v14, 1.0, v15
	ds_write2_b32 v41, v12, v13 offset0:34 offset1:163
	v_mul_f32_e64 v13, |v9|, s38
	v_log_f32_e32 v14, v14
	v_exp_f32_e32 v13, v13
	v_min_f32_e32 v8, 0, v8
	v_min_f32_e32 v9, 0, v9
	v_add_f32_e32 v13, 1.0, v13
	v_add_f32_e32 v0, v23, v0
	v_cmp_gt_f32_e32 vcc, s39, v13
	v_fma_f32 v8, -v14, s40, v8
	v_cndmask_b32_e64 v14, 0, 32, vcc
	v_ldexp_f32 v13, v13, v14
	v_log_f32_e32 v13, v13
	v_cndmask_b32_e32 v14, 0, v125, vcc
	v_mul_f32_e32 v8, 0x3d800000, v8
	v_mul_f32_e64 v4, |v0|, s38
	v_mul_f32_e32 v12, 0x3f317217, v13
	v_fma_f32 v12, v13, s40, -v12
	v_fmac_f32_e32 v12, 0x3377d1cf, v13
	v_fmac_f32_e32 v12, 0x3f317217, v13
	v_cmp_lt_f32_e64 s[0:1], |v13|, s41
	v_exp_f32_e32 v4, v4
	v_add_f32_e32 v1, v23, v1
	v_cndmask_b32_e64 v12, v13, v12, s[0:1]
	v_mul_f32_e64 v13, |v10|, s38
	v_exp_f32_e32 v13, v13
	v_sub_f32_e32 v12, v12, v14
	v_sub_f32_e32 v9, v9, v12
	v_mul_f32_e32 v9, 0x3d800000, v9
	v_add_f32_e32 v12, 1.0, v13
	ds_write2_b32 v42, v8, v9 offset0:48 offset1:177
	v_min_f32_e32 v8, 0, v10
	v_log_f32_e32 v12, v12
	v_add_f32_e32 v10, v23, v11
	v_mul_f32_e64 v11, |v10|, s38
	v_exp_f32_e32 v11, v11
	s_nop 0
	v_add_f32_e32 v11, 1.0, v11
	v_add_f32_e32 v4, 1.0, v4
	v_fma_f32 v8, -v12, s40, v8
	v_log_f32_e32 v11, v11
	v_min_f32_e32 v9, 0, v10
	v_log_f32_e32 v4, v4
	v_fma_f32 v5, -v11, s40, v9
	v_mul_f32_e32 v8, 0x3d800000, v8
	v_mul_f32_e32 v5, 0x3d800000, v5
	ds_write2_b32 v20, v8, v5 offset0:50 offset1:179
	v_mul_f32_e64 v6, |v1|, s38
	v_exp_f32_e32 v6, v6
	v_min_f32_e32 v0, 0, v0
	v_add_f32_e32 v2, v23, v2
	v_add_f32_e32 v5, 1.0, v6
	v_cmp_gt_f32_e32 vcc, s39, v5
	v_fma_f32 v0, -v4, s40, v0
	v_min_f32_e32 v1, 0, v1
	v_cndmask_b32_e64 v6, 0, 32, vcc
	v_ldexp_f32 v5, v5, v6
	v_log_f32_e32 v5, v5
	v_cndmask_b32_e32 v6, 0, v125, vcc
	v_mul_f32_e32 v0, 0x3d800000, v0
	v_add_u32_e32 v41, 0x400, v127
	v_mul_f32_e32 v4, 0x3f317217, v5
	v_fma_f32 v4, v5, s40, -v4
	v_fmac_f32_e32 v4, 0x3377d1cf, v5
	v_fmac_f32_e32 v4, 0x3f317217, v5
	v_cmp_lt_f32_e64 s[0:1], |v5|, s41
	s_nop 1
	v_cndmask_b32_e64 v4, v5, v4, s[0:1]
	v_mul_f32_e64 v5, |v2|, s38
	v_exp_f32_e32 v5, v5
	v_sub_f32_e32 v4, v4, v6
	v_sub_f32_e32 v1, v1, v4
	v_mul_f32_e32 v1, 0x3d800000, v1
	v_add_f32_e32 v4, 1.0, v5
	ds_write2_b32 v21, v0, v1 offset0:64 offset1:193
	v_min_f32_e32 v0, 0, v2
	v_log_f32_e32 v4, v4
	v_add_f32_e32 v2, v23, v3
	v_mul_f32_e64 v3, |v2|, s38
	v_exp_f32_e32 v3, v3
	s_nop 0
	v_add_f32_e32 v3, 1.0, v3
	s_nop 0
	v_fma_f32 v0, -v4, s40, v0
	v_log_f32_e32 v3, v3
	v_min_f32_e32 v1, 0, v2
	v_mul_f32_e32 v0, 0x3d800000, v0
	s_nop 1
	v_fma_f32 v1, -v3, s40, v1
	v_mul_f32_e32 v1, 0x3d800000, v1
	ds_write2_b32 v22, v0, v1 offset0:66 offset1:195
	s_waitcnt lgkmcnt(0)
	s_barrier
	ds_read2_b32 v[0:1], v127 offset1:129
	ds_read2_b32 v[70:71], v41 offset0:2 offset1:131
	ds_read2_b32 v[68:69], v129 offset0:4 offset1:133
	ds_read2_b32 v[66:67], v130 offset0:6 offset1:135
	ds_read2_b32 v[64:65], v132 offset0:8 offset1:137
	ds_read2_b32 v[62:63], v135 offset0:10 offset1:139
	ds_read2_b32 v[60:61], v138 offset0:12 offset1:141
	ds_read2_b32 v[58:59], v133 offset0:14 offset1:143
	ds_read2_b32 v[56:57], v136 offset0:16 offset1:145
	ds_read2_b32 v[54:55], v139 offset0:18 offset1:147
	ds_read2_b32 v[52:53], v141 offset0:20 offset1:149
	ds_read2_b32 v[50:51], v142 offset0:22 offset1:151
	ds_read2_b32 v[48:49], v140 offset0:24 offset1:153
	ds_read2_b32 v[46:47], v137 offset0:26 offset1:155
	ds_read2_b32 v[44:45], v134 offset0:28 offset1:157
	ds_read2_b32 v[42:43], v131 offset0:30 offset1:159
	s_mov_b64 s[0:1], exec
	s_and_b64 s[12:13], s[0:1], s[6:7]
	s_xor_b64 s[0:1], s[12:13], s[0:1]
	s_mov_b64 exec, s[12:13]
	s_cbranch_execz .LBB0_657
	s_waitcnt lgkmcnt(0)
	v_add_f32_e32 v42, v42, v43
	v_add_f32_e32 v29, v45, v42
	v_add_f32_e32 v28, v44, v29
	v_add_f32_e32 v27, v47, v28
	v_add_f32_e32 v26, v46, v27
	v_add_f32_e32 v25, v49, v26
	v_add_f32_e32 v24, v48, v25
	v_add_f32_e32 v23, v51, v24
	v_add_f32_e32 v22, v50, v23
	v_add_f32_e32 v21, v53, v22
	v_add_f32_e32 v20, v52, v21
	v_add_f32_e32 v19, v55, v20
	v_add_f32_e32 v18, v54, v19
	v_add_f32_e32 v17, v57, v18
	v_add_f32_e32 v16, v56, v17
	v_add_f32_e32 v15, v59, v16
	v_add_f32_e32 v14, v58, v15
	v_add_f32_e32 v13, v61, v14
	v_add_f32_e32 v12, v60, v13
	v_add_f32_e32 v11, v63, v12
	v_add_f32_e32 v10, v62, v11
	v_add_f32_e32 v9, v65, v10
	v_add_f32_e32 v8, v64, v9
	v_add_f32_e32 v7, v67, v8
	v_add_f32_e32 v6, v66, v7
	v_add_f32_e32 v5, v69, v6
	v_add_f32_e32 v4, v68, v5
	v_add_f32_e32 v3, v71, v4
	v_add_f32_e32 v2, v70, v3
	v_add_f32_e32 v1, v1, v2
	v_add_f32_e32 v0, v0, v1
	v_mov_b32_e32 v143, v0

.LBB0_824:
	s_or_b64 exec, exec, s[0:1]
	v_add_u32_e32 v20, s60, v34
	v_mov_b32_e32 v21, v31
	v_lshl_add_u64 v[20:21], v[20:21], 2, s[90:91]
	v_mov_b32_e32 v20, v211
	v_mfma_f32_16x16x32_bf16 v[12:15], v[12:15], v[16:19], 0
	v_add_u32_e32 v114, 0x1000, v112
	v_add_u32_e32 v117, 0x1400, v112
	v_add_u32_e32 v120, 0x1800, v112
	v_mfma_f32_16x16x32_bf16 v[8:11], v[8:11], v[16:19], 0
	v_add_u32_e32 v115, 0x1c00, v112
	v_add_u32_e32 v118, 0x2000, v112
	v_add_u32_e32 v121, 0x2400, v112
	v_mfma_f32_16x16x32_bf16 v[4:7], v[4:7], v[16:19], 0
	v_add_u32_e32 v123, 0x2800, v112
	v_add_u32_e32 v124, 0x2c00, v112
	v_add_u32_e32 v122, 0x3000, v112
	v_mfma_f32_16x16x32_bf16 v[0:3], v[0:3], v[16:19], 0
	v_add_u32_e32 v119, 0x3400, v112
	v_add_u32_e32 v116, 0x3800, v112
	v_add_u32_e32 v113, 0x3c00, v112
.Lpf_c_skip:
	v_add_f32_e32 v12, v20, v12
	v_add_f32_e32 v13, v20, v13
	v_min_f32_e32 v21, 0, v12
	v_mul_f32_e64 v12, |v12|, s80
	v_add_f32_e32 v14, v20, v14
	v_min_f32_e32 v22, 0, v13
	v_mul_f32_e64 v13, |v13|, s80
	v_exp_f32_e32 v12, v12
	v_add_f32_e32 v15, v20, v15
	v_min_f32_e32 v23, 0, v14
	v_mul_f32_e64 v14, |v14|, s80
	v_exp_f32_e32 v13, v13
	v_min_f32_e32 v51, 0, v15
	v_mul_f32_e64 v15, |v15|, s80
	v_exp_f32_e32 v14, v14
	v_exp_f32_e32 v15, v15
	v_add_f32_e32 v12, 1.0, v12
	v_add_f32_e32 v8, v20, v8
	v_add_f32_e32 v13, 1.0, v13
	v_min_f32_e32 v53, 0, v8
	v_mul_f32_e64 v8, |v8|, s80
	v_add_f32_e32 v14, 1.0, v14
	v_exp_f32_e32 v8, v8
	v_add_f32_e32 v15, 1.0, v15
	v_log_f32_e32 v12, v12
	v_log_f32_e32 v13, v13
	v_log_f32_e32 v14, v14
	v_add_f32_e32 v8, 1.0, v8
	v_log_f32_e32 v15, v15
	v_log_f32_e32 v8, v8
	v_add_f32_e32 v9, v20, v9
	v_mul_f32_e64 v54, |v9|, s80
	v_exp_f32_e32 v54, v54
	v_fma_f32 v12, -v12, s82, v21
	v_fma_f32 v13, -v13, s82, v22
	v_fma_f32 v14, -v14, s82, v23
	v_fma_f32 v15, -v15, s82, v51
	v_mul_f32_e32 v12, 0x3d800000, v12
	v_mul_f32_e32 v13, 0x3d800000, v13
	v_mul_f32_e32 v14, 0x3d800000, v14
	v_mul_f32_e32 v15, 0x3d800000, v15
	ds_write2_b32 v111, v12, v13 offset0:16 offset1:145
	ds_write2_b32 v24, v14, v15 offset0:18 offset1:147
	v_add_f32_e32 v12, 1.0, v54
	v_add_f32_e32 v10, v20, v10
	v_min_f32_e32 v9, 0, v9
	v_log_f32_e32 v12, v12
	v_fma_f32 v8, -v8, s82, v53
	v_mul_f32_e32 v8, 0x3d800000, v8
	v_mul_f32_e64 v13, |v10|, s80
	v_exp_f32_e32 v13, v13
	v_fma_f32 v9, -v12, s82, v9
	v_mul_f32_e32 v9, 0x3d800000, v9
	v_add_f32_e32 v12, 1.0, v13
	ds_write2_b32 v25, v8, v9 offset0:32 offset1:161
	v_min_f32_e32 v8, 0, v10
	v_log_f32_e32 v12, v12
	v_add_f32_e32 v10, v20, v11
	v_mul_f32_e64 v11, |v10|, s80
	v_exp_f32_e32 v11, v11
	s_nop 0
	v_add_f32_e32 v11, 1.0, v11
	v_add_f32_e32 v4, v20, v4
	v_cmp_gt_f32_e32 vcc, s81, v11
	v_fma_f32 v8, -v12, s82, v8
	v_cndmask_b32_e64 v12, 0, 32, vcc
	v_ldexp_f32 v11, v11, v12
	v_log_f32_e32 v11, v11
	v_min_f32_e32 v9, 0, v10
	v_cndmask_b32_e32 v12, 0, v110, vcc
	v_mul_f32_e32 v8, 0x3d800000, v8
	v_mul_f32_e32 v10, 0x3f317217, v11
	v_fma_f32 v10, v11, s82, -v10
	v_fmac_f32_e32 v10, 0x3377d1cf, v11
	v_fmac_f32_e32 v10, 0x3f317217, v11
	v_cmp_lt_f32_e64 s[0:1], |v11|, s83
	v_add_f32_e32 v5, v20, v5
	v_add_f32_e32 v6, v20, v6
	v_cndmask_b32_e64 v10, v11, v10, s[0:1]
	v_mul_f32_e64 v11, |v4|, s80
	v_exp_f32_e32 v11, v11
	v_sub_f32_e32 v10, v10, v12
	v_sub_f32_e32 v9, v9, v10
	v_mul_f32_e32 v9, 0x3d800000, v9
	v_add_f32_e32 v10, 1.0, v11
	ds_write2_b32 v26, v8, v9 offset0:34 offset1:163
	v_mul_f32_e64 v9, |v5|, s80
	v_log_f32_e32 v10, v10
	v_exp_f32_e32 v9, v9
	v_min_f32_e32 v4, 0, v4
	v_min_f32_e32 v5, 0, v5
	v_add_f32_e32 v9, 1.0, v9
	v_add_f32_e32 v0, v20, v0
	v_cmp_gt_f32_e32 vcc, s81, v9
	v_fma_f32 v4, -v10, s82, v4
	v_cndmask_b32_e64 v10, 0, 32, vcc
	v_ldexp_f32 v9, v9, v10
	v_log_f32_e32 v9, v9
	v_cndmask_b32_e32 v10, 0, v110, vcc
	v_mul_f32_e32 v4, 0x3d800000, v4
	v_add_f32_e32 v1, v20, v1
	v_mul_f32_e32 v8, 0x3f317217, v9
	v_fma_f32 v8, v9, s82, -v8
	v_fmac_f32_e32 v8, 0x3377d1cf, v9
	v_fmac_f32_e32 v8, 0x3f317217, v9
	v_cmp_lt_f32_e64 s[0:1], |v9|, s83
	v_add_f32_e32 v2, v20, v2
	v_add_u32_e32 v51, 0x800, v112
	v_cndmask_b32_e64 v8, v9, v8, s[0:1]
	v_mul_f32_e64 v9, |v6|, s80
	v_exp_f32_e32 v9, v9
	v_sub_f32_e32 v8, v8, v10
	v_sub_f32_e32 v5, v5, v8
	v_mul_f32_e32 v5, 0x3d800000, v5
	v_add_f32_e32 v8, 1.0, v9
	ds_write2_b32 v27, v4, v5 offset0:48 offset1:177
	v_min_f32_e32 v4, 0, v6
	v_log_f32_e32 v8, v8
	v_add_f32_e32 v6, v20, v7
	v_mul_f32_e64 v7, |v6|, s80
	v_exp_f32_e32 v7, v7
	s_nop 0
	v_add_f32_e32 v7, 1.0, v7
	v_add_u32_e32 v53, 0xc00, v112
	v_cmp_gt_f32_e32 vcc, s81, v7
	v_fma_f32 v4, -v8, s82, v4
	v_cndmask_b32_e64 v8, 0, 32, vcc
	v_ldexp_f32 v7, v7, v8
	v_log_f32_e32 v7, v7
	v_min_f32_e32 v5, 0, v6
	v_cndmask_b32_e32 v8, 0, v110, vcc
	v_mul_f32_e32 v4, 0x3d800000, v4
	v_mul_f32_e32 v6, 0x3f317217, v7
	v_fma_f32 v6, v7, s82, -v6
	v_fmac_f32_e32 v6, 0x3377d1cf, v7
	v_fmac_f32_e32 v6, 0x3f317217, v7
	v_cmp_lt_f32_e64 s[0:1], |v7|, s83
	s_nop 1
	v_cndmask_b32_e64 v6, v7, v6, s[0:1]
	v_mul_f32_e64 v7, |v0|, s80
	v_exp_f32_e32 v7, v7
	v_sub_f32_e32 v6, v6, v8
	v_sub_f32_e32 v5, v5, v6
	v_mul_f32_e32 v5, 0x3d800000, v5
	v_add_f32_e32 v6, 1.0, v7
	ds_write2_b32 v28, v4, v5 offset0:50 offset1:179
	v_mul_f32_e64 v5, |v1|, s80
	v_log_f32_e32 v6, v6
	v_exp_f32_e32 v5, v5
	v_min_f32_e32 v0, 0, v0
	v_min_f32_e32 v1, 0, v1
	v_add_f32_e32 v5, 1.0, v5
	s_nop 0
	v_cmp_gt_f32_e32 vcc, s81, v5
	v_fma_f32 v0, -v6, s82, v0
	v_cndmask_b32_e64 v6, 0, 32, vcc
	v_ldexp_f32 v5, v5, v6
	v_log_f32_e32 v5, v5
	v_cndmask_b32_e32 v6, 0, v110, vcc
	v_mul_f32_e32 v0, 0x3d800000, v0
	v_mul_f32_e32 v4, 0x3f317217, v5
	v_fma_f32 v4, v5, s82, -v4
	v_fmac_f32_e32 v4, 0x3377d1cf, v5
	v_fmac_f32_e32 v4, 0x3f317217, v5
	v_cmp_lt_f32_e64 s[0:1], |v5|, s83
	s_nop 1
	v_cndmask_b32_e64 v4, v5, v4, s[0:1]
	v_mul_f32_e64 v5, |v2|, s80
	v_exp_f32_e32 v5, v5
	v_sub_f32_e32 v4, v4, v6
	v_sub_f32_e32 v1, v1, v4
	v_mul_f32_e32 v1, 0x3d800000, v1
	v_add_f32_e32 v4, 1.0, v5
	ds_write2_b32 v29, v0, v1 offset0:64 offset1:193
	v_min_f32_e32 v0, 0, v2
	v_log_f32_e32 v4, v4
	v_add_f32_e32 v2, v20, v3
	v_mul_f32_e64 v3, |v2|, s80
	v_exp_f32_e32 v3, v3
	s_nop 0
	v_add_f32_e32 v3, 1.0, v3
	s_nop 0
	v_fma_f32 v0, -v4, s82, v0
	v_log_f32_e32 v3, v3
	v_min_f32_e32 v1, 0, v2
	v_mul_f32_e32 v0, 0x3d800000, v0
	s_nop 1
	v_fma_f32 v1, -v3, s82, v1
	v_mul_f32_e32 v1, 0x3d800000, v1
	ds_write2_b32 v49, v0, v1 offset0:66 offset1:195
	v_add_u32_e32 v49, 0x400, v112
	s_waitcnt lgkmcnt(0)
	s_barrier
	ds_read2_b32 v[0:1], v112 offset1:129
	ds_read2_b32 v[82:83], v49 offset0:2 offset1:131
	ds_read2_b32 v[80:81], v51 offset0:4 offset1:133
	ds_read2_b32 v[78:79], v53 offset0:6 offset1:135
	ds_read2_b32 v[76:77], v114 offset0:8 offset1:137
	ds_read2_b32 v[74:75], v117 offset0:10 offset1:139
	ds_read2_b32 v[72:73], v120 offset0:12 offset1:141
	ds_read2_b32 v[70:71], v115 offset0:14 offset1:143
	ds_read2_b32 v[68:69], v118 offset0:16 offset1:145
	ds_read2_b32 v[66:67], v121 offset0:18 offset1:147
	ds_read2_b32 v[64:65], v123 offset0:20 offset1:149
	ds_read2_b32 v[62:63], v124 offset0:22 offset1:151
	ds_read2_b32 v[60:61], v122 offset0:24 offset1:153
	ds_read2_b32 v[58:59], v119 offset0:26 offset1:155
	ds_read2_b32 v[56:57], v116 offset0:28 offset1:157
	ds_read2_b32 v[54:55], v113 offset0:30 offset1:159
	s_mov_b64 s[0:1], exec
	s_and_b64 s[46:47], s[0:1], s[6:7]
	s_xor_b64 s[0:1], s[46:47], s[0:1]
	s_mov_b64 exec, s[46:47]
	s_cbranch_execz .LBB0_826
	s_waitcnt lgkmcnt(0)
	v_add_f32_e32 v54, v54, v55
	v_add_f32_e32 v29, v57, v54
	v_add_f32_e32 v28, v56, v29
	v_add_f32_e32 v27, v59, v28
	v_add_f32_e32 v26, v58, v27
	v_add_f32_e32 v25, v61, v26
	v_add_f32_e32 v24, v60, v25
	v_add_f32_e32 v23, v63, v24
	v_add_f32_e32 v22, v62, v23
	v_add_f32_e32 v21, v65, v22
	v_add_f32_e32 v20, v64, v21
	v_add_f32_e32 v19, v67, v20
	v_add_f32_e32 v18, v66, v19
	v_add_f32_e32 v17, v69, v18
	v_add_f32_e32 v16, v68, v17
	v_add_f32_e32 v15, v71, v16
	v_add_f32_e32 v14, v70, v15
	v_add_f32_e32 v13, v73, v14
	v_add_f32_e32 v12, v72, v13
	v_add_f32_e32 v11, v75, v12
	v_add_f32_e32 v10, v74, v11
	v_add_f32_e32 v9, v77, v10
	v_add_f32_e32 v8, v76, v9
	v_add_f32_e32 v7, v79, v8
	v_add_f32_e32 v6, v78, v7
	v_add_f32_e32 v5, v81, v6
	v_add_f32_e32 v4, v80, v5
	v_add_f32_e32 v3, v83, v4
	v_add_f32_e32 v2, v82, v3
	v_add_f32_e32 v1, v1, v2
	v_add_f32_e32 v0, v0, v1
	v_mov_b32_e32 v125, v0
